# v84 plus removal of the three dead lane-mask VALU per chunk that only fed the deleted bpermute-address compares
# speedup vs baseline: 1.0114x; 1.0075x over previous
; #define LAS __attribute__((address_space(3)))
; #define LBAR() do { asm volatile("s_waitcnt lgkmcnt(0)" ::: "memory"); __builtin_amdgcn_s_barrier(); asm volatile("" ::: "memory"); } while (0)
; __device__ __forceinline__ unsigned pk2(float lo, float hi) { return pg8::cvt_pk_bf16(lo, hi); }
; __device__ __forceinline__ void retention_unit(LAS unsigned char* lds, const Ptrs& P, int b, int h, int tid) {
;     ...
;     for (int n = 0; n <= 32; ++n) {
;         LAS unsigned char* bufc = lds + (n & 1) * RSET;
;         LAS bf16* Qs = (LAS bf16*)(bufc + ROFF_Q); LAS bf16* Ks = (LAS bf16*)(bufc + ROFF_K); LAS bf16* K2s = (LAS bf16*)(bufc + ROFF_K2); LAS bf16* Vs = (LAS bf16*)(bufc + ROFF_V);
;         if (n < 32) {
;             *(LAS v4u*)(Qs + lrow * S72 + lseg * 8) = rq; *(LAS v4u*)(Ks + lrow * S72 + lseg * 8) = rk;
;             v4u k2;
; #pragma unroll
;             for (int t = 0; t < 4; ++t) k2[t] = pk2(bflo(rk[t]) * dkey, bfhi(rk[t]) * dkey);
;             *(LAS v4u*)(K2s + lrow * S72 + lseg * 8) = k2;
;             *(LAS v4u*)(Vs + vrow0 * S144 + vseg * 8) = rv0; *(LAS v4u*)(Vs + (vrow0 + 32) * S144 + vseg * 8) = rv1;
;         }
;         if (n >= 1) {
; #pragma unroll
;             for (int it = 0; it < 4; ++it) sgr[it] = __builtin_nontemporal_load((const v2u*)(gsl + ((size_t)(n - 1) * 64 + 16 * it) * 512));
;         }
;         LBAR();
;         if (n + 1 < 32) { const size_t o4 = (size_t)(n + 1) * 64;
;             rq = __builtin_nontemporal_load((const v4u*)(gq + o4 * 256)); rk = __builtin_nontemporal_load((const v4u*)(gk + o4 * 256)); rv0 = __builtin_nontemporal_load((const v4u*)(gv + o4 * 512)); rv1 = __builtin_nontemporal_load((const v4u*)(gv + (o4 + 32) * 512)); }
;         if (n >= 1) {
;             const int row = tid >> 3, sub = tid & 7;
;             const f32x4 pa = *(const LAS f32x4*)(part + (row * 32 + sub * 4) * 2), pb = *(const LAS f32x4*)(part + (row * 32 + sub * 4) * 2 + 4);
;             float s1 = (pa[0] + pa[2]) + (pb[0] + pb[2]), s2 = (pa[1] + pa[3]) + (pb[1] + pb[3]);
; #pragma unroll
;             for (int x = 1; x < 8; x <<= 1) { s1 += __shfl_xor(s1, x); s2 += __shfl_xor(s2, x); }
;             if (sub == 0) { const float mean = s1 * (1.f / 128.f); float var = s2 * (1.f / 128.f) - mean * mean; var = var < 0.f ? 0.f : var;
;                 stat[row * 2] = mean; stat[row * 2 + 1] = __builtin_amdgcn_rsqf(var + 1e-5f); }
.LBB0_658:
	s_add_i32 s89, s89, 1
	s_bitcmp1_b32 s89, 0
	s_cselect_b32 s18, 0xb400, 0
	s_add_i32 s90, s18, 0
	v_add3_u32 v52, s90, v163, v72
	s_waitcnt vmcnt(7)
	ds_write_b128 v52, v[36:39]
	s_waitcnt vmcnt(6)
	ds_write_b128 v52, v[24:27] offset:9216
	v_lshlrev_b32_e32 v36, 16, v24
	v_and_b32_e32 v37, 0xffff0000, v24
	v_pk_mul_f32 v[36:37], v[102:103], v[36:37]
	v_add_u32_e32 v56, 0, v159
	v_cvt_pk_bf16_f32 v24, v36, v37
	v_lshlrev_b32_e32 v36, 16, v25
	v_and_b32_e32 v37, 0xffff0000, v25
	v_pk_mul_f32 v[36:37], v[102:103], v[36:37]
	v_add_u32_e32 v139, 0x1d400, v56
	v_cvt_pk_bf16_f32 v25, v36, v37
	v_lshlrev_b32_e32 v36, 16, v26
	v_and_b32_e32 v37, 0xffff0000, v26
	v_pk_mul_f32 v[36:37], v[102:103], v[36:37]
	v_cvt_pk_bf16_f32 v26, v36, v37
	v_lshlrev_b32_e32 v36, 16, v27
	v_and_b32_e32 v37, 0xffff0000, v27
	v_pk_mul_f32 v[36:37], v[102:103], v[36:37]
	v_cvt_pk_bf16_f32 v27, v36, v37
	ds_write_b128 v52, v[24:27] offset:18432
	v_add3_u32 v24, s90, v158, v84
	s_waitcnt vmcnt(5)
	ds_write_b128 v24, v[28:31] offset:27648
	s_waitcnt vmcnt(4)
	ds_write_b128 v24, v[32:35] offset:36864
	v_lshl_add_u64 v[24:25], s[26:27], 0, v[116:117]
	v_lshl_add_u64 v[24:25], v[24:25], 0, s[12:13]
	v_add_co_u32_e32 v26, vcc, s58, v24
	s_nop 0
	v_addc_co_u32_e32 v27, vcc, 0, v25, vcc
	v_add_co_u32_e32 v28, vcc, s59, v24
	s_nop 1
	v_addc_co_u32_e32 v29, vcc, 0, v25, vcc
	v_add_co_u32_e32 v30, vcc, s60, v24
	s_nop 1
	v_addc_co_u32_e32 v31, vcc, 0, v25, vcc
	v_add_co_u32_e32 v24, vcc, s61, v24
	s_nop 1
	v_addc_co_u32_e32 v25, vcc, 0, v25, vcc
	v_mov_b32_e32 v54, v252
	v_mov_b32_e32 v55, v253
	v_mov_b32_e32 v52, v254
	v_mov_b32_e32 v53, v255
	v_mov_b32_e32 v122, v248
	v_mov_b32_e32 v123, v249
	v_mov_b32_e32 v118, v214
	v_mov_b32_e32 v119, v215
	global_load_dwordx2 v[252:253], v[26:27], off nt
	global_load_dwordx2 v[254:255], v[28:29], off nt
	global_load_dwordx2 v[248:249], v[30:31], off nt
	global_load_dwordx2 v[214:215], v[24:25], off nt
	v_lshl_add_u64 v[24:25], s[26:27], 0, v[110:111]
	v_add_co_u32_e32 v26, vcc, s62, v24
	v_lshl_add_u64 v[28:29], s[26:27], 0, v[112:113]
	s_nop 0
	v_addc_co_u32_e32 v27, vcc, 0, v25, vcc
	v_add_co_u32_e32 v24, vcc, s63, v24
	s_waitcnt lgkmcnt(0)
	s_barrier
	v_lshl_add_u32 v213, v155, 1, s90
	v_add_u32_e32 v75, v213, v62
	v_add_u32_e32 v213, v213, v179
	ds_read_b128 v[216:219], v213 offset:9216
	ds_read_b128 v[220:223], v213 offset:9280
	ds_read_b128 v[188:191], v75
	ds_read_b128 v[192:195], v75 offset:64
	s_nop 0
	v_addc_co_u32_e32 v25, vcc, 0, v25, vcc
	v_add_co_u32_e32 v30, vcc, s64, v28
	global_load_dwordx4 v[36:39], v[26:27], off nt
	s_nop 0
	global_load_dwordx4 v[24:27], v[24:25], off nt
	v_addc_co_u32_e32 v31, vcc, 0, v29, vcc
	v_add_co_u32_e32 v32, vcc, s65, v28
	s_nop 1
	v_addc_co_u32_e32 v33, vcc, 0, v29, vcc
	global_load_dwordx4 v[28:31], v[30:31], off nt
	s_nop 0
	global_load_dwordx4 v[32:35], v[32:33], off nt
	ds_read_b128 v[56:59], v139
	ds_read_b128 v[184:187], v139 offset:16
	s_waitcnt lgkmcnt(1)
	v_pk_add_f32 v[56:57], v[56:57], v[58:59]
	s_waitcnt lgkmcnt(0)
	v_pk_add_f32 v[58:59], v[184:185], v[186:187]
	v_pk_add_f32 v[56:57], v[56:57], v[58:59]
	s_nop 1
	v_add_f32_dpp v56, v56, v56 quad_perm:[1,0,3,2] row_mask:0xf bank_mask:0xf
	v_add_f32_dpp v57, v57, v57 quad_perm:[1,0,3,2] row_mask:0xf bank_mask:0xf
	s_nop 1
	v_add_f32_dpp v56, v56, v56 quad_perm:[2,3,0,1] row_mask:0xf bank_mask:0xf
	v_add_f32_dpp v57, v57, v57 quad_perm:[2,3,0,1] row_mask:0xf bank_mask:0xf
	s_nop 1
	v_add_f32_dpp v56, v56, v56 row_half_mirror row_mask:0xf bank_mask:0xf
	v_add_f32_dpp v57, v57, v57 row_half_mirror row_mask:0xf bank_mask:0xf
	s_and_saveexec_b64 s[18:19], s[0:1]
	s_cbranch_execz .LBB0_657
	s_waitcnt lgkmcnt(0)
	v_add_u32_e32 v58, 0, v198
	v_pk_mul_f32 v[56:57], v[56:57], s[6:7] op_sel_hi:[1,0]
	v_add_u32_e32 v58, 0x21400, v58
	v_fma_f32 v57, -v56, v56, v57
	v_cmp_ngt_f32_e32 vcc, 0, v57
	s_nop 1
	v_cndmask_b32_e32 v57, 0, v57, vcc
	v_add_f32_e32 v57, 0x3727c5ac, v57
	v_rsq_f32_e32 v57, v57
	ds_write2_b32 v58, v56, v57 offset1:1
	s_branch .LBB0_657
